# GEMM unit start: accumulator zeroing with v_mov_b64 (64 instead of 127 moves per tile) on top of the epilogue latency edits
# speedup vs baseline: 1.0033x; 1.0003x over previous
; template <class Epi>
; __device__ __forceinline__ void gemm_phase(LAS unsigned char* lds, const bf16_t* A0, const bf16_t* B0, const bf16_t* A1, const bf16_t* B1, const int K, const Order& S, const Epi& E) {
;     ...
;         const bool has_next = S.next(ui + 1, nxt);
;         const size_t nko = (has_next && nxt.ks > 0) ? (size_t)nxt.ks * ntq * kstep : 0;
;         const char* nA = has_next ? (const char*)(nxt.gid ? A1 : A0) + (size_t)nxt.pm * tstep + nko : cA; const char* nB = has_next ? (const char*)(nxt.gid ? B1 : B0) + (size_t)nxt.pn * tstep + nko : cB;
;     ...
; #pragma unroll
;         for (int a = 0; a < 2; ++a)
; #pragma unroll
;             for (int b = 0; b < 2; ++b)
; #pragma unroll
;                 for (int m = 0; m < 4; ++m)
; #pragma unroll
;                     for (int n = 0; n < 2; ++n) acc[a][b][m][n] = (f32x4){0.f, 0.f, 0.f, 0.f};
;         cur = nxt; cA = nA; cB = nB; ++ui;
.LBB0_216:
	v_readlane_b32 s68, v243, 39
	v_readlane_b32 s80, v243, 51
	v_readlane_b32 s81, v243, 52
	v_readlane_b32 s82, v243, 53
	v_readlane_b32 s83, v243, 54
	s_mov_b64 s[28:29], s[80:81]
	s_xor_b64 s[0:1], s[22:23], -1
	s_mov_b64 s[30:31], s[82:83]
	s_add_u32 s26, s30, s50
	s_addc_u32 s50, s31, s51
	s_add_u32 s42, s30, s42
	s_addc_u32 s43, s31, s43
	s_ashr_i32 s61, s60, 31
	s_mov_b64 s[22:23], s[4:5]
	s_lshl_b64 s[4:5], s[60:61], 20
	s_add_u32 s62, s42, s4
	s_addc_u32 s63, s43, s5
	s_ashr_i32 s59, s58, 31
	s_lshl_b64 s[4:5], s[58:59], 20
	s_add_u32 s18, s26, s4
	s_addc_u32 s19, s50, s5
	s_cmpk_lt_i32 s7, 0xce0
	s_cselect_b64 s[28:29], -1, 0
	s_and_b64 s[4:5], s[28:29], exec
	s_cselect_b32 s7, s63, s21
	s_cselect_b32 s26, s62, s20
	s_cselect_b32 s50, s19, s45
	s_cselect_b32 s51, s18, s44
	s_add_u32 s4, s20, 0x80080
	s_addc_u32 s5, s21, 0
	s_add_u32 s44, s44, 0x100
	v_mov_b32_e32 v0, 0
	s_addc_u32 s45, s45, 0
	s_mov_b32 s52, -2
	v_mov_b32_e32 v1, v0
	v_mov_b64_e32 v[2:3], 0
	v_mov_b64_e32 v[4:5], 0
	v_mov_b64_e32 v[6:7], 0
	v_mov_b64_e32 v[16:17], 0
	v_mov_b64_e32 v[18:19], 0
	v_mov_b64_e32 v[20:21], 0
	v_mov_b64_e32 v[22:23], 0
	v_mov_b64_e32 v[32:33], 0
	v_mov_b64_e32 v[34:35], 0
	v_mov_b64_e32 v[36:37], 0
	v_mov_b64_e32 v[38:39], 0
	v_mov_b64_e32 v[48:49], 0
	v_mov_b64_e32 v[50:51], 0
	v_mov_b64_e32 v[52:53], 0
	v_mov_b64_e32 v[54:55], 0
	v_mov_b64_e32 v[8:9], 0
	v_mov_b64_e32 v[10:11], 0
	v_mov_b64_e32 v[12:13], 0
	v_mov_b64_e32 v[14:15], 0
	v_mov_b64_e32 v[24:25], 0
	v_mov_b64_e32 v[26:27], 0
	v_mov_b64_e32 v[28:29], 0
	v_mov_b64_e32 v[30:31], 0
	v_mov_b64_e32 v[40:41], 0
	v_mov_b64_e32 v[42:43], 0
	v_mov_b64_e32 v[44:45], 0
	v_mov_b64_e32 v[46:47], 0
	v_mov_b64_e32 v[56:57], 0
	v_mov_b64_e32 v[58:59], 0
	v_mov_b64_e32 v[60:61], 0
	v_mov_b64_e32 v[62:63], 0
	v_mov_b64_e32 v[64:65], 0
	v_mov_b64_e32 v[66:67], 0
	v_mov_b64_e32 v[68:69], 0
	v_mov_b64_e32 v[70:71], 0
	v_mov_b64_e32 v[80:81], 0
	v_mov_b64_e32 v[82:83], 0
	v_mov_b64_e32 v[84:85], 0
	v_mov_b64_e32 v[86:87], 0
	v_mov_b64_e32 v[112:113], 0
	v_mov_b64_e32 v[114:115], 0
	v_mov_b64_e32 v[116:117], 0
	v_mov_b64_e32 v[118:119], 0
	v_mov_b64_e32 v[128:129], 0
	v_mov_b64_e32 v[130:131], 0
	v_mov_b64_e32 v[132:133], 0
	v_mov_b64_e32 v[134:135], 0
	v_mov_b64_e32 v[72:73], 0
	v_mov_b64_e32 v[74:75], 0
	v_mov_b64_e32 v[76:77], 0
	v_mov_b64_e32 v[78:79], 0
	v_mov_b64_e32 v[88:89], 0
	v_mov_b64_e32 v[90:91], 0
	v_mov_b64_e32 v[96:97], 0
	v_mov_b64_e32 v[98:99], 0
	v_mov_b64_e32 v[120:121], 0
	v_mov_b64_e32 v[122:123], 0
	v_mov_b64_e32 v[124:125], 0
	v_mov_b64_e32 v[126:127], 0
	v_mov_b64_e32 v[136:137], 0
	v_mov_b64_e32 v[138:139], 0
	v_mov_b64_e32 v[140:141], 0
	v_mov_b64_e32 v[142:143], 0
	v_readlane_b32 s69, v243, 40
	v_readlane_b32 s70, v243, 41
	v_readlane_b32 s71, v243, 42
	v_readlane_b32 s72, v243, 43
	v_readlane_b32 s73, v243, 44
	v_readlane_b32 s74, v243, 45
	v_readlane_b32 s75, v243, 46
	v_readlane_b32 s76, v243, 47
	v_readlane_b32 s77, v243, 48
	v_readlane_b32 s78, v243, 49
	v_readlane_b32 s79, v243, 50

; template <class Epi>
; __device__ __forceinline__ void gemm_phase(LAS unsigned char* lds, const bf16_t* A0, const bf16_t* B0, const bf16_t* A1, const bf16_t* B1, const int K, const Order& S, const Epi& E) {
;     ...
; #pragma unroll
;         for (int a = 0; a < 2; ++a)
; #pragma unroll
;             for (int b = 0; b < 2; ++b)
; #pragma unroll
;                 for (int m = 0; m < 4; ++m)
; #pragma unroll
;                     for (int n = 0; n < 2; ++n) acc[a][b][m][n] = (f32x4){0.f, 0.f, 0.f, 0.f};
.LBB0_755:
	s_ashr_i32 s25, s24, 31
	s_lshl_b64 s[40:41], s[24:25], 20
	s_add_u32 s12, s56, s40
	s_addc_u32 s13, s57, s41
	s_ashr_i32 s27, s26, 31
	s_lshl_b64 s[42:43], s[26:27], 20
	v_readlane_b32 s18, v243, 27
	v_readlane_b32 s19, v243, 28
	s_add_u32 s18, s18, s42
	s_addc_u32 s19, s19, s43
	s_cmpk_lt_i32 s11, 0x440
	s_cselect_b64 s[28:29], -1, 0
	s_and_b64 s[54:55], s[28:29], exec
	s_cselect_b32 s11, s13, s51
	s_cselect_b32 s27, s12, s50
	s_cselect_b32 s39, s19, s53
	s_cselect_b32 s47, s18, s52
	s_add_u32 s50, s50, 0x80080
	s_addc_u32 s51, s51, 0
	s_add_u32 s74, s52, 0x100
	v_mov_b32_e32 v0, 0
	s_addc_u32 s75, s53, 0
	s_mov_b32 s76, -2
	s_waitcnt lgkmcnt(0)
	v_mov_b32_e32 v1, v0
	v_mov_b64_e32 v[2:3], 0
	v_mov_b64_e32 v[4:5], 0
	v_mov_b64_e32 v[6:7], 0
	v_mov_b64_e32 v[8:9], 0
	v_mov_b64_e32 v[10:11], 0
	v_mov_b64_e32 v[16:17], 0
	v_mov_b64_e32 v[18:19], 0
	v_mov_b64_e32 v[24:25], 0
	v_mov_b64_e32 v[26:27], 0
	v_mov_b64_e32 v[32:33], 0
	v_mov_b64_e32 v[34:35], 0
	v_mov_b64_e32 v[44:45], 0
	v_mov_b64_e32 v[46:47], 0
	v_mov_b64_e32 v[52:53], 0
	v_mov_b64_e32 v[54:55], 0
	v_mov_b64_e32 v[12:13], 0
	s_waitcnt lgkmcnt(0)
	v_mov_b64_e32 v[14:15], 0
	v_mov_b64_e32 v[20:21], 0
	v_mov_b64_e32 v[22:23], 0
	v_mov_b64_e32 v[28:29], 0
	v_mov_b64_e32 v[30:31], 0
	v_mov_b64_e32 v[36:37], 0
	v_mov_b64_e32 v[38:39], 0
	v_mov_b64_e32 v[40:41], 0
	v_mov_b64_e32 v[42:43], 0
	v_mov_b64_e32 v[48:49], 0
	v_mov_b64_e32 v[50:51], 0
	v_mov_b64_e32 v[56:57], 0
	v_mov_b64_e32 v[58:59], 0
	v_mov_b64_e32 v[60:61], 0
	v_mov_b64_e32 v[62:63], 0
	v_mov_b64_e32 v[64:65], 0
	v_mov_b64_e32 v[66:67], 0
	v_mov_b64_e32 v[68:69], 0
	v_mov_b64_e32 v[70:71], 0
	v_mov_b64_e32 v[72:73], 0
	v_mov_b64_e32 v[74:75], 0
	v_mov_b64_e32 v[80:81], 0
	v_mov_b64_e32 v[82:83], 0
	s_waitcnt vmcnt(0)
	v_mov_b64_e32 v[88:89], 0
	v_mov_b64_e32 v[90:91], 0
	v_mov_b64_e32 v[92:93], 0
	v_mov_b64_e32 v[94:95], 0
	v_mov_b64_e32 v[104:105], 0
	v_mov_b64_e32 v[106:107], 0
	v_mov_b64_e32 v[108:109], 0
	v_mov_b64_e32 v[110:111], 0
	v_mov_b64_e32 v[76:77], 0
	v_mov_b64_e32 v[78:79], 0
	v_mov_b64_e32 v[84:85], 0
	v_mov_b64_e32 v[86:87], 0
	v_mov_b64_e32 v[96:97], 0
	v_mov_b64_e32 v[98:99], 0
	v_mov_b64_e32 v[100:101], 0
	v_mov_b64_e32 v[102:103], 0
	v_mov_b64_e32 v[112:113], 0
	v_mov_b64_e32 v[114:115], 0
	v_mov_b64_e32 v[116:117], 0
	v_mov_b64_e32 v[118:119], 0
	v_mov_b64_e32 v[120:121], 0
	v_mov_b64_e32 v[122:123], 0
	v_mov_b64_e32 v[124:125], 0
	v_mov_b64_e32 v[126:127], 0

; template <class Epi>
; __device__ __forceinline__ void gemm_phase(LAS unsigned char* lds, const bf16_t* A0, const bf16_t* B0, const bf16_t* A1, const bf16_t* B1, const int K, const Order& S, const Epi& E) {
;     ...
; #pragma unroll
;         for (int a = 0; a < 2; ++a)
; #pragma unroll
;             for (int b = 0; b < 2; ++b)
; #pragma unroll
;                 for (int m = 0; m < 4; ++m)
; #pragma unroll
;                     for (int n = 0; n < 2; ++n) acc[a][b][m][n] = (f32x4){0.f, 0.f, 0.f, 0.f};
.LBB0_863:
	s_ashr_i32 s37, s36, 31
	s_lshl_b64 s[38:39], s[36:37], 20
	s_add_u32 s38, s88, s38
	s_addc_u32 s39, s89, s39
	s_ashr_i32 s27, s26, 31
	s_lshl_b64 s[40:41], s[26:27], 20
	v_readlane_b32 s18, v243, 29
	v_readlane_b32 s19, v243, 30
	s_add_u32 s40, s18, s40
	s_addc_u32 s41, s19, s41
	s_cmpk_lt_i32 s5, 0x220
	s_cselect_b64 s[42:43], -1, 0
	s_and_b64 s[52:53], s[42:43], exec
	s_cselect_b32 s5, s39, s47
	s_cselect_b32 s27, s38, s46
	s_cselect_b32 s37, s41, s51
	s_cselect_b32 s68, s40, s50
	s_add_u32 s46, s46, 0x80080
	s_addc_u32 s47, s47, 0
	s_add_u32 s69, s50, 0x100
	v_mov_b32_e32 v0, 0
	s_addc_u32 s70, s51, 0
	s_mov_b32 s71, -2
	v_mov_b32_e32 v1, v0
	v_mov_b64_e32 v[2:3], 0
	v_mov_b64_e32 v[4:5], 0
	v_mov_b64_e32 v[6:7], 0
	v_mov_b64_e32 v[16:17], 0
	v_mov_b64_e32 v[18:19], 0
	v_mov_b64_e32 v[20:21], 0
	v_mov_b64_e32 v[22:23], 0
	v_mov_b64_e32 v[32:33], 0
	v_mov_b64_e32 v[34:35], 0
	v_mov_b64_e32 v[36:37], 0
	v_mov_b64_e32 v[38:39], 0
	v_mov_b64_e32 v[48:49], 0
	v_mov_b64_e32 v[50:51], 0
	v_mov_b64_e32 v[52:53], 0
	v_mov_b64_e32 v[54:55], 0
	v_mov_b64_e32 v[8:9], 0
	v_mov_b64_e32 v[10:11], 0
	v_mov_b64_e32 v[12:13], 0
	v_mov_b64_e32 v[14:15], 0
	v_mov_b64_e32 v[24:25], 0
	v_mov_b64_e32 v[26:27], 0
	v_mov_b64_e32 v[28:29], 0
	v_mov_b64_e32 v[30:31], 0
	v_mov_b64_e32 v[40:41], 0
	v_mov_b64_e32 v[42:43], 0
	v_mov_b64_e32 v[44:45], 0
	v_mov_b64_e32 v[46:47], 0
	v_mov_b64_e32 v[56:57], 0
	v_mov_b64_e32 v[58:59], 0
	v_mov_b64_e32 v[60:61], 0
	v_mov_b64_e32 v[62:63], 0
	v_mov_b64_e32 v[64:65], 0
	v_mov_b64_e32 v[66:67], 0
	v_mov_b64_e32 v[68:69], 0
	v_mov_b64_e32 v[70:71], 0
	v_mov_b64_e32 v[80:81], 0
	v_mov_b64_e32 v[82:83], 0
	s_waitcnt vmcnt(0)
	v_mov_b64_e32 v[84:85], 0
	v_mov_b64_e32 v[86:87], 0
	v_mov_b64_e32 v[96:97], 0
	v_mov_b64_e32 v[98:99], 0
	v_mov_b64_e32 v[100:101], 0
	v_mov_b64_e32 v[102:103], 0
	v_mov_b64_e32 v[112:113], 0
	v_mov_b64_e32 v[114:115], 0
	v_mov_b64_e32 v[116:117], 0
	v_mov_b64_e32 v[118:119], 0
	v_mov_b64_e32 v[72:73], 0
	v_mov_b64_e32 v[74:75], 0
	v_mov_b64_e32 v[76:77], 0
	v_mov_b64_e32 v[78:79], 0
	v_mov_b64_e32 v[88:89], 0
	v_mov_b64_e32 v[90:91], 0
	v_mov_b64_e32 v[92:93], 0
	v_mov_b64_e32 v[94:95], 0
	v_mov_b64_e32 v[104:105], 0
	v_mov_b64_e32 v[106:107], 0
	v_mov_b64_e32 v[108:109], 0
	v_mov_b64_e32 v[110:111], 0
	v_mov_b64_e32 v[120:121], 0
	v_mov_b64_e32 v[122:123], 0
	v_mov_b64_e32 v[124:125], 0
	v_mov_b64_e32 v[126:127], 0

; template <class Epi>
; __device__ __forceinline__ void gemm_phase(LAS unsigned char* lds, const bf16_t* A0, const bf16_t* B0, const bf16_t* A1, const bf16_t* B1, const int K, const Order& S, const Epi& E) {
;     ...
; #pragma unroll
;         for (int a = 0; a < 2; ++a)
; #pragma unroll
;             for (int b = 0; b < 2; ++b)
; #pragma unroll
;                 for (int m = 0; m < 4; ++m)
; #pragma unroll
;                     for (int n = 0; n < 2; ++n) acc[a][b][m][n] = (f32x4){0.f, 0.f, 0.f, 0.f};
.LBB0_1045:
	s_ashr_i32 s27, s26, 31
	s_lshl_b64 s[36:37], s[26:27], 19
	v_readlane_b32 s12, v243, 33
	v_readlane_b32 s13, v243, 34
	s_add_u32 s36, s12, s36
	s_addc_u32 s37, s13, s37
	s_ashr_i32 s23, s22, 31
	s_lshl_b64 s[38:39], s[22:23], 19
	v_readlane_b32 s40, v243, 31
	v_readlane_b32 s41, v243, 32
	s_add_u32 s38, s40, s38
	s_addc_u32 s39, s41, s39
	s_cmpk_lt_i32 s9, 0x440
	s_cselect_b64 s[40:41], -1, 0
	s_and_b64 s[50:51], s[40:41], exec
	s_cselect_b32 s9, s37, s45
	s_cselect_b32 s23, s36, s44
	s_cselect_b32 s27, s39, s47
	s_cselect_b32 s43, s38, s46
	s_add_u32 s44, s44, 0x40080
	s_addc_u32 s45, s45, 0
	s_add_u32 s69, s46, 0x100
	v_mov_b32_e32 v0, 0
	s_addc_u32 s70, s47, 0
	s_mov_b32 s71, -2
	s_waitcnt lgkmcnt(0)
	v_mov_b32_e32 v1, v0
	v_mov_b64_e32 v[2:3], 0
	v_mov_b64_e32 v[4:5], 0
	v_mov_b64_e32 v[6:7], 0
	v_mov_b64_e32 v[12:13], 0
	v_mov_b64_e32 v[14:15], 0
	v_mov_b64_e32 v[20:21], 0
	v_mov_b64_e32 v[22:23], 0
	v_mov_b64_e32 v[28:29], 0
	v_mov_b64_e32 v[30:31], 0
	v_mov_b64_e32 v[36:37], 0
	v_mov_b64_e32 v[38:39], 0
	v_mov_b64_e32 v[44:45], 0
	v_mov_b64_e32 v[46:47], 0
	v_mov_b64_e32 v[52:53], 0
	v_mov_b64_e32 v[54:55], 0
	v_mov_b64_e32 v[8:9], 0
	v_mov_b64_e32 v[10:11], 0
	v_mov_b64_e32 v[16:17], 0
	v_mov_b64_e32 v[18:19], 0
	v_mov_b64_e32 v[24:25], 0
	v_mov_b64_e32 v[26:27], 0
	v_mov_b64_e32 v[32:33], 0
	v_mov_b64_e32 v[34:35], 0
	v_mov_b64_e32 v[40:41], 0
	v_mov_b64_e32 v[42:43], 0
	v_mov_b64_e32 v[48:49], 0
	v_mov_b64_e32 v[50:51], 0
	v_mov_b64_e32 v[56:57], 0
	v_mov_b64_e32 v[58:59], 0
	v_mov_b64_e32 v[60:61], 0
	v_mov_b64_e32 v[62:63], 0
	v_mov_b64_e32 v[64:65], 0
	v_mov_b64_e32 v[66:67], 0
	v_mov_b64_e32 v[68:69], 0
	v_mov_b64_e32 v[70:71], 0
	v_mov_b64_e32 v[76:77], 0
	v_mov_b64_e32 v[78:79], 0
	s_waitcnt vmcnt(0)
	v_mov_b64_e32 v[84:85], 0
	v_mov_b64_e32 v[86:87], 0
	v_mov_b64_e32 v[92:93], 0
	v_mov_b64_e32 v[94:95], 0
	v_mov_b64_e32 v[100:101], 0
	v_mov_b64_e32 v[102:103], 0
	v_mov_b64_e32 v[104:105], 0
	v_mov_b64_e32 v[106:107], 0
	v_mov_b64_e32 v[108:109], 0
	v_mov_b64_e32 v[110:111], 0
	v_mov_b64_e32 v[72:73], 0
	v_mov_b64_e32 v[74:75], 0
	v_mov_b64_e32 v[80:81], 0
	v_mov_b64_e32 v[82:83], 0
	v_mov_b64_e32 v[88:89], 0
	v_mov_b64_e32 v[90:91], 0
	v_mov_b64_e32 v[96:97], 0
	v_mov_b64_e32 v[98:99], 0
	v_mov_b64_e32 v[112:113], 0
	v_mov_b64_e32 v[114:115], 0
	v_mov_b64_e32 v[116:117], 0
	v_mov_b64_e32 v[118:119], 0
	v_mov_b64_e32 v[120:121], 0
	v_mov_b64_e32 v[122:123], 0
	v_mov_b64_e32 v[124:125], 0
	v_mov_b64_e32 v[126:127], 0

; template <class Epi>
; __device__ __forceinline__ void gemm_phase(LAS unsigned char* lds, const bf16_t* A0, const bf16_t* B0, const bf16_t* A1, const bf16_t* B1, const int K, const Order& S, const Epi& E) {
;     ...
; #pragma unroll
;         for (int a = 0; a < 2; ++a)
; #pragma unroll
;             for (int b = 0; b < 2; ++b)
; #pragma unroll
;                 for (int m = 0; m < 4; ++m)
; #pragma unroll
;                     for (int n = 0; n < 2; ++n) acc[a][b][m][n] = (f32x4){0.f, 0.f, 0.f, 0.f};
.LBB0_1153:
	s_ashr_i32 s63, s62, 31
	s_lshl_b64 s[12:13], s[62:63], 20
	s_add_u32 s64, s88, s12
	s_addc_u32 s65, s89, s13
	s_ashr_i32 s61, s60, 31
	s_lshl_b64 s[12:13], s[60:61], 20
	v_readlane_b32 s66, v243, 21
	v_readlane_b32 s67, v243, 22
	s_add_u32 s66, s66, s12
	s_addc_u32 s67, s67, s13
	s_cmpk_lt_i32 s1, 0x1760
	s_cselect_b64 s[68:69], -1, 0
	s_and_b64 s[12:13], s[68:69], exec
	s_cselect_b32 s1, s65, s9
	s_cselect_b32 s61, s64, s8
	s_cselect_b32 s63, s67, s11
	s_cselect_b32 s71, s66, s10
	s_add_u32 s8, s8, 0x80080
	s_addc_u32 s9, s9, 0
	s_add_u32 s72, s10, 0x100
	v_mov_b32_e32 v0, 0
	s_addc_u32 s73, s11, 0
	s_mov_b32 s74, -2
	v_mov_b32_e32 v1, v0
	v_mov_b64_e32 v[2:3], 0
	v_mov_b64_e32 v[4:5], 0
	v_mov_b64_e32 v[6:7], 0
	v_mov_b64_e32 v[8:9], 0
	v_mov_b64_e32 v[10:11], 0
	v_mov_b64_e32 v[12:13], 0
	v_mov_b64_e32 v[14:15], 0
	v_mov_b64_e32 v[16:17], 0
	v_mov_b64_e32 v[18:19], 0
	v_mov_b64_e32 v[20:21], 0
	v_mov_b64_e32 v[22:23], 0
	v_mov_b64_e32 v[32:33], 0
	v_mov_b64_e32 v[34:35], 0
	v_mov_b64_e32 v[36:37], 0
	v_mov_b64_e32 v[38:39], 0
	v_mov_b64_e32 v[56:57], 0
	v_mov_b64_e32 v[58:59], 0
	v_mov_b64_e32 v[60:61], 0
	v_mov_b64_e32 v[62:63], 0
	v_mov_b64_e32 v[24:25], 0
	v_mov_b64_e32 v[26:27], 0
	v_mov_b64_e32 v[28:29], 0
	v_mov_b64_e32 v[30:31], 0
	v_mov_b64_e32 v[40:41], 0
	v_mov_b64_e32 v[42:43], 0
	v_mov_b64_e32 v[44:45], 0
	v_mov_b64_e32 v[46:47], 0
	v_mov_b64_e32 v[48:49], 0
	v_mov_b64_e32 v[50:51], 0
	v_mov_b64_e32 v[52:53], 0
	v_mov_b64_e32 v[54:55], 0
	s_waitcnt vmcnt(0)
	v_mov_b64_e32 v[112:113], 0
	v_mov_b64_e32 v[114:115], 0
	v_mov_b64_e32 v[116:117], 0
	v_mov_b64_e32 v[118:119], 0
	v_mov_b64_e32 v[120:121], 0
	v_mov_b64_e32 v[122:123], 0
	v_mov_b64_e32 v[124:125], 0
	v_mov_b64_e32 v[126:127], 0
	v_mov_b64_e32 v[136:137], 0
	v_mov_b64_e32 v[138:139], 0
	v_mov_b64_e32 v[140:141], 0
	v_mov_b64_e32 v[142:143], 0
	v_mov_b64_e32 v[88:89], 0
	v_mov_b64_e32 v[90:91], 0
	v_mov_b64_e32 v[92:93], 0
	v_mov_b64_e32 v[94:95], 0
	v_mov_b64_e32 v[64:65], 0
	v_mov_b64_e32 v[66:67], 0
	v_mov_b64_e32 v[68:69], 0
	v_mov_b64_e32 v[70:71], 0
	v_mov_b64_e32 v[128:129], 0
	v_mov_b64_e32 v[130:131], 0
	v_mov_b64_e32 v[132:133], 0
	v_mov_b64_e32 v[134:135], 0
	v_mov_b64_e32 v[144:145], 0
	v_mov_b64_e32 v[146:147], 0
	v_mov_b64_e32 v[148:149], 0
	v_mov_b64_e32 v[150:151], 0
	v_mov_b64_e32 v[96:97], 0
	v_mov_b64_e32 v[98:99], 0
	v_mov_b64_e32 v[100:101], 0
	v_mov_b64_e32 v[102:103], 0

; template <class Epi>
; __device__ __forceinline__ void gemm_phase(LAS unsigned char* lds, const bf16_t* A0, const bf16_t* B0, const bf16_t* A1, const bf16_t* B1, const int K, const Order& S, const Epi& E) {
;     ...
;         const int cnt = cur.ks < 0 ? nt : ntq;
;     ...
; #pragma unroll
;         for (int a = 0; a < 2; ++a)
; #pragma unroll
;             for (int b = 0; b < 2; ++b)
; #pragma unroll
;                 for (int m = 0; m < 4; ++m)
; #pragma unroll
;                     for (int n = 0; n < 2; ++n) acc[a][b][m][n] = (f32x4){0.f, 0.f, 0.f, 0.f};
.LBB0_1333:
	s_cmp_lt_i32 s35, 0
	s_cselect_b32 s50, 0x58, 22
	s_add_i32 s51, s50, -2
	s_add_u32 s24, s24, 0x160080
	s_addc_u32 s25, s25, 0
	s_add_u32 s52, s26, 0x100
	v_mov_b32_e32 v0, 0
	s_mov_b32 s30, 0
	s_addc_u32 s53, s27, 0
	v_mov_b32_e32 v1, v0
	v_mov_b64_e32 v[2:3], 0
	v_mov_b64_e32 v[4:5], 0
	v_mov_b64_e32 v[6:7], 0
	v_mov_b64_e32 v[8:9], 0
	v_mov_b64_e32 v[10:11], 0
	v_mov_b64_e32 v[12:13], 0
	v_mov_b64_e32 v[14:15], 0
	v_mov_b64_e32 v[16:17], 0
	v_mov_b64_e32 v[18:19], 0
	v_mov_b64_e32 v[20:21], 0
	v_mov_b64_e32 v[22:23], 0
	v_mov_b64_e32 v[28:29], 0
	v_mov_b64_e32 v[30:31], 0
	v_mov_b64_e32 v[36:37], 0
	v_mov_b64_e32 v[38:39], 0
	v_mov_b64_e32 v[24:25], 0
	v_mov_b64_e32 v[26:27], 0
	v_mov_b64_e32 v[32:33], 0
	v_mov_b64_e32 v[34:35], 0
	v_mov_b64_e32 v[40:41], 0
	v_mov_b64_e32 v[42:43], 0
	v_mov_b64_e32 v[44:45], 0
	v_mov_b64_e32 v[46:47], 0
	v_mov_b64_e32 v[48:49], 0
	v_mov_b64_e32 v[50:51], 0
	v_mov_b64_e32 v[52:53], 0
	v_mov_b64_e32 v[54:55], 0
	v_mov_b64_e32 v[56:57], 0
	v_mov_b64_e32 v[58:59], 0
	v_mov_b64_e32 v[60:61], 0
	v_mov_b64_e32 v[62:63], 0
	v_mov_b64_e32 v[64:65], 0
	v_mov_b64_e32 v[66:67], 0
	v_mov_b64_e32 v[68:69], 0
	v_mov_b64_e32 v[70:71], 0
	v_mov_b64_e32 v[72:73], 0
	v_mov_b64_e32 v[74:75], 0
	v_mov_b64_e32 v[76:77], 0
	v_mov_b64_e32 v[78:79], 0
	v_mov_b64_e32 v[80:81], 0
	v_mov_b64_e32 v[82:83], 0
	s_waitcnt vmcnt(0)
	v_mov_b64_e32 v[88:89], 0
	v_mov_b64_e32 v[90:91], 0
	v_mov_b64_e32 v[96:97], 0
	v_mov_b64_e32 v[98:99], 0
	v_mov_b64_e32 v[104:105], 0
	v_mov_b64_e32 v[106:107], 0
	v_mov_b64_e32 v[84:85], 0
	v_mov_b64_e32 v[86:87], 0
	v_mov_b64_e32 v[92:93], 0
	v_mov_b64_e32 v[94:95], 0
	v_mov_b64_e32 v[100:101], 0
	v_mov_b64_e32 v[102:103], 0
	v_mov_b64_e32 v[108:109], 0
	v_mov_b64_e32 v[110:111], 0
	v_mov_b64_e32 v[112:113], 0
	v_mov_b64_e32 v[114:115], 0
	v_mov_b64_e32 v[116:117], 0
	v_mov_b64_e32 v[118:119], 0
	v_mov_b64_e32 v[120:121], 0
	v_mov_b64_e32 v[122:123], 0
	v_mov_b64_e32 v[124:125], 0
	v_mov_b64_e32 v[126:127], 0
